# P2 input-projection GEMM epilogue stores made write-through (sc1) on top of batched rg3 carry chains
# speedup vs baseline: 1.0359x; 1.0071x over previous
.LBB0_258:
	v_or_b32_e32 v138, s8, v142
	v_add_u32_e32 v146, s46, v140
	v_ashrrev_i32_e32 v139, 31, v138
	v_ashrrev_i32_e32 v144, 31, v146
	v_lshl_add_u64 v[138:139], v[138:139], 1, s[4:5]
	v_mul_lo_u32 v147, s44, v144
	v_mul_lo_u32 v148, s45, v146
	v_mad_u64_u32 v[144:145], s[4:5], s44, v146, 0
	v_add3_u32 v145, v145, v147, v148
	v_lshl_add_u64 v[144:145], v[144:145], 1, v[138:139]
	v_cvt_pk_bf16_f32 v124, v124, v125
	v_cvt_pk_bf16_f32 v125, v126, v127
	v_cvt_pk_bf16_f32 v126, v120, v121
	v_cvt_pk_bf16_f32 v127, v122, v123
	global_store_dwordx4 v[144:145], v[124:127], off sc1
	v_cvt_pk_bf16_f32 v116, v116, v117
	v_cvt_pk_bf16_f32 v117, v118, v119
	v_cvt_pk_bf16_f32 v118, v108, v109
	v_add_u32_e32 v108, 16, v146
	v_ashrrev_i32_e32 v109, 31, v108
	v_cvt_pk_bf16_f32 v119, v110, v111
	v_mul_lo_u32 v110, s44, v109
	v_mul_lo_u32 v111, s45, v108
	v_mad_u64_u32 v[108:109], s[4:5], s44, v108, 0
	v_add3_u32 v109, v109, v110, v111
	global_store_dwordx4 v[144:145], v[116:119], off offset:256 sc1
	s_and_b64 vcc, exec, s[40:41]
	s_nop 0
	v_lshl_add_u64 v[116:117], v[108:109], 1, v[138:139]
	v_cvt_pk_bf16_f32 v108, v112, v113
	v_cvt_pk_bf16_f32 v109, v114, v115
	v_cvt_pk_bf16_f32 v110, v104, v105
	v_cvt_pk_bf16_f32 v111, v106, v107
	global_store_dwordx4 v[116:117], v[108:111], off sc1
	v_cvt_pk_bf16_f32 v100, v100, v101
	v_cvt_pk_bf16_f32 v101, v102, v103
	v_cvt_pk_bf16_f32 v102, v92, v93
	v_add_u32_e32 v92, 32, v146
	v_ashrrev_i32_e32 v93, 31, v92
	v_cvt_pk_bf16_f32 v103, v94, v95
	v_mul_lo_u32 v94, s44, v93
	v_mul_lo_u32 v95, s45, v92
	v_mad_u64_u32 v[92:93], s[4:5], s44, v92, 0
	v_add3_u32 v93, v93, v94, v95
	global_store_dwordx4 v[116:117], v[100:103], off offset:256 sc1
	s_nop 1
	v_lshl_add_u64 v[100:101], v[92:93], 1, v[138:139]
	v_cvt_pk_bf16_f32 v92, v96, v97
	v_cvt_pk_bf16_f32 v93, v98, v99
	v_cvt_pk_bf16_f32 v94, v88, v89
	v_cvt_pk_bf16_f32 v95, v90, v91
	global_store_dwordx4 v[100:101], v[92:95], off sc1
	v_cvt_pk_bf16_f32 v84, v84, v85
	v_cvt_pk_bf16_f32 v85, v86, v87
	v_cvt_pk_bf16_f32 v86, v76, v77
	v_add_u32_e32 v76, 48, v146
	v_ashrrev_i32_e32 v77, 31, v76
	v_cvt_pk_bf16_f32 v87, v78, v79
	v_mul_lo_u32 v78, s44, v77
	v_mul_lo_u32 v79, s45, v76
	v_mad_u64_u32 v[76:77], s[4:5], s44, v76, 0
	v_add3_u32 v77, v77, v78, v79
	global_store_dwordx4 v[100:101], v[84:87], off offset:256 sc1
	s_nop 1
	v_lshl_add_u64 v[84:85], v[76:77], 1, v[138:139]
	v_cvt_pk_bf16_f32 v76, v80, v81
	v_cvt_pk_bf16_f32 v77, v82, v83
	v_cvt_pk_bf16_f32 v78, v72, v73
	v_cvt_pk_bf16_f32 v79, v74, v75
	global_store_dwordx4 v[84:85], v[76:79], off sc1
	v_cvt_pk_bf16_f32 v68, v68, v69
	v_cvt_pk_bf16_f32 v69, v70, v71
	v_cvt_pk_bf16_f32 v70, v64, v65
	v_add_u32_e32 v64, 0x80, v146
	v_ashrrev_i32_e32 v65, 31, v64
	v_cvt_pk_bf16_f32 v71, v66, v67
	v_mul_lo_u32 v66, s44, v65
	v_mul_lo_u32 v67, s45, v64
	v_mad_u64_u32 v[64:65], s[4:5], s44, v64, 0
	v_add3_u32 v65, v65, v66, v67
	v_lshl_add_u64 v[64:65], v[64:65], 1, v[138:139]
	global_store_dwordx4 v[84:85], v[68:71], off offset:256 sc1
	v_cvt_pk_bf16_f32 v60, v60, v61
	v_cvt_pk_bf16_f32 v61, v62, v63
	v_cvt_pk_bf16_f32 v62, v56, v57
	v_cvt_pk_bf16_f32 v63, v58, v59
	global_store_dwordx4 v[64:65], v[60:63], off sc1
	v_cvt_pk_bf16_f32 v52, v52, v53
	v_cvt_pk_bf16_f32 v53, v54, v55
	v_cvt_pk_bf16_f32 v54, v44, v45
	v_add_u32_e32 v44, 0x90, v146
	v_ashrrev_i32_e32 v45, 31, v44
	v_cvt_pk_bf16_f32 v55, v46, v47
	v_mul_lo_u32 v46, s44, v45
	v_mul_lo_u32 v47, s45, v44
	v_mad_u64_u32 v[44:45], s[4:5], s44, v44, 0
	v_add3_u32 v45, v45, v46, v47
	global_store_dwordx4 v[64:65], v[52:55], off offset:256 sc1
	s_nop 1
	v_lshl_add_u64 v[52:53], v[44:45], 1, v[138:139]
	v_cvt_pk_bf16_f32 v44, v48, v49
	v_cvt_pk_bf16_f32 v45, v50, v51
	v_cvt_pk_bf16_f32 v46, v40, v41
	v_cvt_pk_bf16_f32 v47, v42, v43
	global_store_dwordx4 v[52:53], v[44:47], off sc1
	v_cvt_pk_bf16_f32 v36, v36, v37
	v_cvt_pk_bf16_f32 v37, v38, v39
	v_cvt_pk_bf16_f32 v38, v28, v29
	v_add_u32_e32 v28, 0xa0, v146
	v_ashrrev_i32_e32 v29, 31, v28
	v_cvt_pk_bf16_f32 v39, v30, v31
	v_mul_lo_u32 v30, s44, v29
	v_mul_lo_u32 v31, s45, v28
	v_mad_u64_u32 v[28:29], s[4:5], s44, v28, 0
	v_add3_u32 v29, v29, v30, v31
	global_store_dwordx4 v[52:53], v[36:39], off offset:256 sc1
	s_nop 1
	v_lshl_add_u64 v[36:37], v[28:29], 1, v[138:139]
	v_cvt_pk_bf16_f32 v28, v32, v33
	v_cvt_pk_bf16_f32 v29, v34, v35
	v_cvt_pk_bf16_f32 v30, v24, v25
	v_cvt_pk_bf16_f32 v31, v26, v27
	global_store_dwordx4 v[36:37], v[28:31], off sc1
	v_cvt_pk_bf16_f32 v20, v20, v21
	v_cvt_pk_bf16_f32 v21, v22, v23
	v_cvt_pk_bf16_f32 v22, v12, v13
	v_add_u32_e32 v12, 0xb0, v146
	v_ashrrev_i32_e32 v13, 31, v12
	v_cvt_pk_bf16_f32 v23, v14, v15
	v_mul_lo_u32 v14, s44, v13
	v_mul_lo_u32 v15, s45, v12
	v_mad_u64_u32 v[12:13], s[4:5], s44, v12, 0
	v_add3_u32 v13, v13, v14, v15
	global_store_dwordx4 v[36:37], v[20:23], off offset:256 sc1
	s_mov_b64 s[4:5], -1
	s_nop 0
	v_lshl_add_u64 v[20:21], v[12:13], 1, v[138:139]
	v_cvt_pk_bf16_f32 v12, v16, v17
	v_cvt_pk_bf16_f32 v13, v18, v19
	v_cvt_pk_bf16_f32 v14, v8, v9
	v_cvt_pk_bf16_f32 v15, v10, v11
	global_store_dwordx4 v[20:21], v[12:15], off sc1
	v_cvt_pk_bf16_f32 v4, v4, v5
	v_cvt_pk_bf16_f32 v5, v6, v7
	v_cvt_pk_bf16_f32 v6, v0, v1
	v_cvt_pk_bf16_f32 v7, v2, v3
	global_store_dwordx4 v[20:21], v[4:7], off offset:256 sc1
	s_cbranch_vccnz .LBB0_239
	s_andn2_b64 vcc, exec, s[0:1]
	s_cbranch_vccnz .LBB0_238
	s_barrier
	s_branch .LBB0_238
